# k40 + modulation GEMM skips the 48 MFMAs per K iteration whose accumulators belong to all-padding row blocks (never stored)
# speedup vs baseline: 1.0079x; 1.0079x over previous
; #define PG8_STAGE(bufoff, gbase, voff) do { _Pragma("unroll") for (int _i = 0; _i < 2; ++_i) \
;         __builtin_amdgcn_global_load_lds((const unsigned*)((const char*)(gbase) + (voff)[_i]), (LAS unsigned*)(lds + (bufoff) + ldsw + _i * 8192), 16, 0, 0); } while (0)
; #define PG8_LDA(dst, b, h) do { _Pragma("unroll") for (int m = 0; m < 4; ++m) _Pragma("unroll") for (int k = 0; k < 2; ++k) dst[m][k] = *(const LAS bf16x8*)(lds + PG8_SA(b, h) + aoff + m * 2048 + k * 1024); } while (0)
; #define PG8_LDB(dst, b, h) do { _Pragma("unroll") for (int n = 0; n < 2; ++n) _Pragma("unroll") for (int k = 0; k < 2; ++k) dst[n][k] = *(const LAS bf16x8*)(lds + PG8_SB(b, h) + boff + n * 2048 + k * 1024); } while (0)
; #define PG8_MMA(ai, bj, At, Bt) do { __builtin_amdgcn_s_setprio(1); _Pragma("unroll") for (int m = 0; m < 4; ++m) _Pragma("unroll") for (int n = 0; n < 2; ++n) _Pragma("unroll") for (int k = 0; k < 2; ++k) \
;         acc[ai][bj][m][n] = __builtin_amdgcn_mfma_f32_16x16x32_bf16(Bt[n][k], At[m][k], acc[ai][bj][m][n], 0, 0, 0); __builtin_amdgcn_s_setprio(0); } while (0)
; #define PG8_WAIT_V(n) asm volatile("s_waitcnt vmcnt(" #n ")" ::: "memory")
; #define PG8_WAIT_L(n) asm volatile("s_waitcnt lgkmcnt(" #n ")" ::: "memory")
; #define PG8_BAR __builtin_amdgcn_s_barrier()
; #define PG8_SCHED __builtin_amdgcn_sched_barrier(0)
; template <class Epi, bool ALIGN_EPI>
; __device__ __forceinline__ void gemm_phase(LAS unsigned char* lds, const Gemm g, const Order& S, const Epi& E, const int wave_id) {
;     ...
;             PG8_LDB(B0, 0, 0); PG8_LDB(B1, 0, 1); PG8_SCHED; PG8_LDA(At, 0, 0); PG8_STAGE(PG8_SA(1, 1), a1 + hstepA, voffA);
;             PG8_WAIT_V(8); PG8_WAIT_L(0); PG8_BAR; PG8_MMA(0, 0, At, B0); PG8_MMA(0, 1, At, B1); PG8_BAR; PG8_SCHED;
;             PG8_LDA(At, 0, 1); PG8_STAGE(PG8_SB(0, 0), b2, voffB); PG8_STAGE(PG8_SB(0, 1), b2 + hstepB, voffB); PG8_STAGE(PG8_SA(0, 0), a2, voffA);
;             PG8_WAIT_V(8); PG8_WAIT_L(0); PG8_BAR; PG8_MMA(1, 0, At, B0); PG8_MMA(1, 1, At, B1); PG8_BAR; PG8_SCHED;
.LBB0_227:
	ds_read_b128 v[140:143], v148
	ds_read_b128 v[152:155], v148 offset:1024
	ds_read_b128 v[156:159], v148 offset:2048
	ds_read_b128 v[160:163], v148 offset:3072
	ds_read_b128 v[164:167], v149
	ds_read_b128 v[168:171], v149 offset:1024
	ds_read_b128 v[172:175], v149 offset:2048
	ds_read_b128 v[176:179], v149 offset:3072
	s_add_u32 s22, s20, 0x100
	s_addc_u32 s23, s21, 0
	s_add_u32 s24, s17, s20
	s_addc_u32 s25, s19, s21
	s_cmp_eq_u32 s52, 12
	s_cselect_b32 s26, 0, s22
	s_cselect_b32 s27, 0, s23
	s_cselect_b32 s24, s2, s24
	s_cselect_b32 s25, s3, s25
	s_add_u32 s26, s4, s26
	s_addc_u32 s27, s5, s27
	v_lshl_add_u64 v[212:213], v[132:133], 0, s[20:21]
	s_add_i32 m0, s36, 0xc000
	ds_read_b128 v[180:183], v150
	ds_read_b128 v[184:187], v150 offset:1024
	ds_read_b128 v[188:191], v150 offset:2048
	ds_read_b128 v[192:195], v150 offset:3072
	ds_read_b128 v[196:199], v150 offset:4096
	ds_read_b128 v[200:203], v150 offset:5120
	ds_read_b128 v[204:207], v150 offset:6144
	ds_read_b128 v[208:211], v150 offset:7168
	global_load_lds_dwordx4 v[212:213], off
	v_lshl_add_u64 v[212:213], v[134:135], 0, s[20:21]
	s_add_i32 m0, s36, 0xe000
	s_nop 0
	global_load_lds_dwordx4 v[212:213], off
	s_waitcnt vmcnt(8)
	s_waitcnt lgkmcnt(0)
	s_barrier
	s_setprio 1
	s_waitcnt lgkmcnt(0)
	v_mfma_f32_16x16x32_bf16 v[124:127], v[140:143], v[180:183], v[124:127]
	v_mfma_f32_16x16x32_bf16 v[120:123], v[156:159], v[180:183], v[120:123]
	v_mfma_f32_16x16x32_bf16 v[108:111], v[140:143], v[188:191], v[108:111]
	v_mfma_f32_16x16x32_bf16 v[104:107], v[156:159], v[188:191], v[104:107]
	v_mfma_f32_16x16x32_bf16 v[92:95], v[140:143], v[196:199], v[92:95]
	v_mfma_f32_16x16x32_bf16 v[88:91], v[156:159], v[196:199], v[88:91]
	v_mfma_f32_16x16x32_bf16 v[76:79], v[140:143], v[204:207], v[76:79]
	v_mfma_f32_16x16x32_bf16 v[72:75], v[156:159], v[204:207], v[72:75]
	v_mfma_f32_16x16x32_bf16 v[124:127], v[152:155], v[184:187], v[124:127]
	v_mfma_f32_16x16x32_bf16 v[120:123], v[160:163], v[184:187], v[120:123]
	v_mfma_f32_16x16x32_bf16 v[108:111], v[152:155], v[192:195], v[108:111]
	v_mfma_f32_16x16x32_bf16 v[104:107], v[160:163], v[192:195], v[104:107]
	v_mfma_f32_16x16x32_bf16 v[92:95], v[152:155], v[200:203], v[92:95]
	v_mfma_f32_16x16x32_bf16 v[88:91], v[160:163], v[200:203], v[88:91]
	v_mfma_f32_16x16x32_bf16 v[76:79], v[152:155], v[208:211], v[76:79]
	v_mfma_f32_16x16x32_bf16 v[72:75], v[160:163], v[208:211], v[72:75]
	s_setprio 0
	s_setprio 1
	v_mfma_f32_16x16x32_bf16 v[116:119], v[164:167], v[180:183], v[116:119]
	v_mfma_f32_16x16x32_bf16 v[112:115], v[172:175], v[180:183], v[112:115]
	v_mfma_f32_16x16x32_bf16 v[100:103], v[164:167], v[188:191], v[100:103]
	v_mfma_f32_16x16x32_bf16 v[96:99], v[172:175], v[188:191], v[96:99]
	v_mfma_f32_16x16x32_bf16 v[84:87], v[164:167], v[196:199], v[84:87]
	v_mfma_f32_16x16x32_bf16 v[80:83], v[172:175], v[196:199], v[80:83]
	v_mfma_f32_16x16x32_bf16 v[68:71], v[164:167], v[204:207], v[68:71]
	v_mfma_f32_16x16x32_bf16 v[64:67], v[172:175], v[204:207], v[64:67]
	v_mfma_f32_16x16x32_bf16 v[116:119], v[168:171], v[184:187], v[116:119]
	v_mfma_f32_16x16x32_bf16 v[112:115], v[176:179], v[184:187], v[112:115]
	v_mfma_f32_16x16x32_bf16 v[100:103], v[168:171], v[192:195], v[100:103]
	v_mfma_f32_16x16x32_bf16 v[96:99], v[176:179], v[192:195], v[96:99]
	v_mfma_f32_16x16x32_bf16 v[84:87], v[168:171], v[200:203], v[84:87]
	v_mfma_f32_16x16x32_bf16 v[80:83], v[176:179], v[200:203], v[80:83]
	v_mfma_f32_16x16x32_bf16 v[68:71], v[168:171], v[208:211], v[68:71]
	v_mfma_f32_16x16x32_bf16 v[64:67], v[176:179], v[208:211], v[64:67]
	s_setprio 0
	s_barrier
	s_add_i32 s20, s47, s35
	v_lshl_add_u64 v[212:213], s[24:25], 0, v[128:129]
	s_mov_b32 m0, s20
	ds_read_b128 v[180:183], v150 offset:16384
	ds_read_b128 v[184:187], v150 offset:17408
	ds_read_b128 v[188:191], v150 offset:18432
	ds_read_b128 v[192:195], v150 offset:19456
	ds_read_b128 v[196:199], v150 offset:20480
	ds_read_b128 v[200:203], v150 offset:21504
	ds_read_b128 v[204:207], v150 offset:22528
	ds_read_b128 v[208:211], v150 offset:23552
	global_load_lds_dwordx4 v[212:213], off
	s_add_i32 m0, s20, 0x2000
	s_add_u32 s20, s24, 0x40000
	v_lshl_add_u64 v[214:215], s[24:25], 0, v[130:131]
	s_addc_u32 s21, s25, 0
	s_add_i32 s53, s48, s35
	global_load_lds_dwordx4 v[214:215], off
	v_lshl_add_u64 v[216:217], s[20:21], 0, v[128:129]
	s_mov_b32 m0, s53
	v_lshl_add_u64 v[218:219], s[26:27], 0, v[130:131]
	global_load_lds_dwordx4 v[216:217], off
	v_lshl_add_u64 v[216:217], s[20:21], 0, v[130:131]
	s_add_i32 m0, s53, 0x2000
	s_nop 0
	global_load_lds_dwordx4 v[216:217], off
	v_lshl_add_u64 v[216:217], s[26:27], 0, v[128:129]
	s_mov_b32 m0, s36
	s_nop 0
	global_load_lds_dwordx4 v[216:217], off
	s_mov_b32 m0, s37
	s_nop 0
	global_load_lds_dwordx4 v[218:219], off
	s_waitcnt vmcnt(8)
	s_waitcnt lgkmcnt(0)
	s_barrier
	s_setprio 1
	s_waitcnt lgkmcnt(0)
	v_mfma_f32_16x16x32_bf16 v[60:63], v[140:143], v[180:183], v[60:63]
	v_mfma_f32_16x16x32_bf16 v[56:59], v[156:159], v[180:183], v[56:59]
	v_mfma_f32_16x16x32_bf16 v[60:63], v[152:155], v[184:187], v[60:63]
	v_mfma_f32_16x16x32_bf16 v[56:59], v[160:163], v[184:187], v[56:59]
	s_setprio 0
	s_setprio 1
	v_mfma_f32_16x16x32_bf16 v[52:55], v[164:167], v[180:183], v[52:55]
	v_mfma_f32_16x16x32_bf16 v[48:51], v[172:175], v[180:183], v[48:51]
	v_mfma_f32_16x16x32_bf16 v[52:55], v[168:171], v[184:187], v[52:55]
	v_mfma_f32_16x16x32_bf16 v[48:51], v[176:179], v[184:187], v[48:51]
	s_setprio 0
	s_barrier
; #define PG8_STAGE(bufoff, gbase, voff) do { _Pragma("unroll") for (int _i = 0; _i < 2; ++_i) \
;         __builtin_amdgcn_global_load_lds((const unsigned*)((const char*)(gbase) + (voff)[_i]), (LAS unsigned*)(lds + (bufoff) + ldsw + _i * 8192), 16, 0, 0); } while (0)
; #define PG8_LDA(dst, b, h) do { _Pragma("unroll") for (int m = 0; m < 4; ++m) _Pragma("unroll") for (int k = 0; k < 2; ++k) dst[m][k] = *(const LAS bf16x8*)(lds + PG8_SA(b, h) + aoff + m * 2048 + k * 1024); } while (0)
; #define PG8_LDB(dst, b, h) do { _Pragma("unroll") for (int n = 0; n < 2; ++n) _Pragma("unroll") for (int k = 0; k < 2; ++k) dst[n][k] = *(const LAS bf16x8*)(lds + PG8_SB(b, h) + boff + n * 2048 + k * 1024); } while (0)
; #define PG8_MMA(ai, bj, At, Bt) do { __builtin_amdgcn_s_setprio(1); _Pragma("unroll") for (int m = 0; m < 4; ++m) _Pragma("unroll") for (int n = 0; n < 2; ++n) _Pragma("unroll") for (int k = 0; k < 2; ++k) \
;         acc[ai][bj][m][n] = __builtin_amdgcn_mfma_f32_16x16x32_bf16(Bt[n][k], At[m][k], acc[ai][bj][m][n], 0, 0, 0); __builtin_amdgcn_s_setprio(0); } while (0)
; #define PG8_WAIT_V(n) asm volatile("s_waitcnt vmcnt(" #n ")" ::: "memory")
; #define PG8_WAIT_L(n) asm volatile("s_waitcnt lgkmcnt(" #n ")" ::: "memory")
; #define PG8_BAR __builtin_amdgcn_s_barrier()
; #define PG8_SCHED __builtin_amdgcn_sched_barrier(0)
; template <class Epi, bool ALIGN_EPI>
; __device__ __forceinline__ void gemm_phase(LAS unsigned char* lds, const Gemm g, const Order& S, const Epi& E, const int wave_id) {
;     ...
;             PG8_LDB(B0, 1, 0); PG8_LDB(B1, 1, 1); PG8_SCHED; PG8_LDA(At, 1, 0); PG8_STAGE(PG8_SA(0, 1), a2 + hstepA, voffA);
;             PG8_WAIT_V(8); PG8_WAIT_L(0); PG8_BAR; PG8_MMA(0, 0, At, B0); PG8_MMA(0, 1, At, B1); PG8_BAR; PG8_SCHED;
;             PG8_LDA(At, 1, 1); PG8_STAGE(PG8_SB(1, 0), b3, voffB); PG8_STAGE(PG8_SB(1, 1), b3 + hstepB, voffB); PG8_STAGE(PG8_SA(1, 0), a3, voffA);
;             PG8_WAIT_V(8); PG8_WAIT_L(0); PG8_BAR; PG8_MMA(1, 0, At, B0); PG8_MMA(1, 1, At, B1); PG8_BAR; PG8_SCHED;
	s_add_i32 s53, 0, 0x18000
	v_add_u32_e32 v151, s53, v147
	s_add_i32 s54, 0, 0x1c000
	ds_read_b128 v[140:143], v151
	ds_read_b128 v[152:155], v151 offset:1024
	ds_read_b128 v[156:159], v151 offset:2048
	ds_read_b128 v[160:163], v151 offset:3072
	v_add_u32_e32 v151, s54, v147
	ds_read_b128 v[164:167], v151
	ds_read_b128 v[168:171], v151 offset:1024
	ds_read_b128 v[172:175], v151 offset:2048
	ds_read_b128 v[176:179], v151 offset:3072
	s_add_u32 s20, s26, 0x40000
	s_addc_u32 s21, s27, 0
	s_mov_b32 m0, s38
	v_lshl_add_u64 v[220:221], s[20:21], 0, v[128:129]
	ds_read_b128 v[180:183], v150 offset:32768
	ds_read_b128 v[184:187], v150 offset:33792
	ds_read_b128 v[188:191], v150 offset:34816
	ds_read_b128 v[192:195], v150 offset:35840
	ds_read_b128 v[196:199], v150 offset:36864
	ds_read_b128 v[200:203], v150 offset:37888
	ds_read_b128 v[204:207], v150 offset:38912
	ds_read_b128 v[208:211], v150 offset:39936
	global_load_lds_dwordx4 v[220:221], off
	v_lshl_add_u64 v[220:221], s[20:21], 0, v[130:131]
	s_mov_b32 m0, s39
	s_nop 0
	global_load_lds_dwordx4 v[220:221], off
	s_waitcnt vmcnt(8)
	s_waitcnt lgkmcnt(0)
	s_barrier
	s_setprio 1
	s_waitcnt lgkmcnt(0)
	v_mfma_f32_16x16x32_bf16 v[124:127], v[140:143], v[180:183], v[124:127]
	v_mfma_f32_16x16x32_bf16 v[120:123], v[156:159], v[180:183], v[120:123]
	v_mfma_f32_16x16x32_bf16 v[108:111], v[140:143], v[188:191], v[108:111]
	v_mfma_f32_16x16x32_bf16 v[104:107], v[156:159], v[188:191], v[104:107]
	v_mfma_f32_16x16x32_bf16 v[92:95], v[140:143], v[196:199], v[92:95]
	v_mfma_f32_16x16x32_bf16 v[88:91], v[156:159], v[196:199], v[88:91]
	v_mfma_f32_16x16x32_bf16 v[76:79], v[140:143], v[204:207], v[76:79]
	v_mfma_f32_16x16x32_bf16 v[72:75], v[156:159], v[204:207], v[72:75]
	v_mfma_f32_16x16x32_bf16 v[124:127], v[152:155], v[184:187], v[124:127]
	v_mfma_f32_16x16x32_bf16 v[120:123], v[160:163], v[184:187], v[120:123]
	v_mfma_f32_16x16x32_bf16 v[108:111], v[152:155], v[192:195], v[108:111]
	v_mfma_f32_16x16x32_bf16 v[104:107], v[160:163], v[192:195], v[104:107]
	v_mfma_f32_16x16x32_bf16 v[92:95], v[152:155], v[200:203], v[92:95]
	v_mfma_f32_16x16x32_bf16 v[88:91], v[160:163], v[200:203], v[88:91]
	v_mfma_f32_16x16x32_bf16 v[76:79], v[152:155], v[208:211], v[76:79]
	v_mfma_f32_16x16x32_bf16 v[72:75], v[160:163], v[208:211], v[72:75]
	s_setprio 0
	s_setprio 1
	v_mfma_f32_16x16x32_bf16 v[116:119], v[164:167], v[180:183], v[116:119]
	v_mfma_f32_16x16x32_bf16 v[112:115], v[172:175], v[180:183], v[112:115]
	v_mfma_f32_16x16x32_bf16 v[100:103], v[164:167], v[188:191], v[100:103]
	v_mfma_f32_16x16x32_bf16 v[96:99], v[172:175], v[188:191], v[96:99]
	v_mfma_f32_16x16x32_bf16 v[84:87], v[164:167], v[196:199], v[84:87]
	v_mfma_f32_16x16x32_bf16 v[80:83], v[172:175], v[196:199], v[80:83]
	v_mfma_f32_16x16x32_bf16 v[68:71], v[164:167], v[204:207], v[68:71]
	v_mfma_f32_16x16x32_bf16 v[64:67], v[172:175], v[204:207], v[64:67]
	v_mfma_f32_16x16x32_bf16 v[116:119], v[168:171], v[184:187], v[116:119]
	v_mfma_f32_16x16x32_bf16 v[112:115], v[176:179], v[184:187], v[112:115]
	v_mfma_f32_16x16x32_bf16 v[100:103], v[168:171], v[192:195], v[100:103]
	v_mfma_f32_16x16x32_bf16 v[96:99], v[176:179], v[192:195], v[96:99]
	v_mfma_f32_16x16x32_bf16 v[84:87], v[168:171], v[200:203], v[84:87]
	v_mfma_f32_16x16x32_bf16 v[80:83], v[176:179], v[200:203], v[80:83]
	v_mfma_f32_16x16x32_bf16 v[68:71], v[168:171], v[208:211], v[68:71]
	v_mfma_f32_16x16x32_bf16 v[64:67], v[176:179], v[208:211], v[64:67]
	s_setprio 0
	s_barrier
	s_add_i32 s20, s53, s35
	v_lshl_add_u64 v[212:213], v[212:213], 0, s[12:13]
	s_mov_b32 m0, s20
	ds_read_b128 v[180:183], v150 offset:49152
	ds_read_b128 v[184:187], v150 offset:50176
	ds_read_b128 v[188:191], v150 offset:51200
	ds_read_b128 v[192:195], v150 offset:52224
	ds_read_b128 v[196:199], v150 offset:53248
	ds_read_b128 v[200:203], v150 offset:54272
	ds_read_b128 v[204:207], v150 offset:55296
	ds_read_b128 v[208:211], v150 offset:56320
	global_load_lds_dwordx4 v[212:213], off
	s_add_i32 m0, s20, 0x2000
	s_add_u32 s20, s24, 0x40080
	v_lshl_add_u64 v[212:213], v[214:215], 0, s[12:13]
	s_addc_u32 s21, s25, 0
	s_add_i32 s24, s54, s35
	global_load_lds_dwordx4 v[212:213], off
	v_lshl_add_u64 v[212:213], s[20:21], 0, v[128:129]
	s_mov_b32 m0, s24
	s_nop 0
	global_load_lds_dwordx4 v[212:213], off
	v_lshl_add_u64 v[212:213], s[20:21], 0, v[130:131]
	s_add_i32 m0, s24, 0x2000
	s_nop 0
	global_load_lds_dwordx4 v[212:213], off
	v_lshl_add_u64 v[212:213], v[216:217], 0, s[12:13]
	s_mov_b32 m0, s44
	s_nop 0
	global_load_lds_dwordx4 v[212:213], off
	v_lshl_add_u64 v[212:213], v[218:219], 0, s[12:13]
	s_mov_b32 m0, s45
	s_nop 0
	global_load_lds_dwordx4 v[212:213], off
	s_waitcnt vmcnt(8)
	s_waitcnt lgkmcnt(0)
	s_barrier
	s_setprio 1
	s_waitcnt lgkmcnt(0)
	v_mfma_f32_16x16x32_bf16 v[60:63], v[140:143], v[180:183], v[60:63]
	v_mfma_f32_16x16x32_bf16 v[56:59], v[156:159], v[180:183], v[56:59]
	v_mfma_f32_16x16x32_bf16 v[60:63], v[152:155], v[184:187], v[60:63]
	v_mfma_f32_16x16x32_bf16 v[56:59], v[160:163], v[184:187], v[56:59]
	s_setprio 0
	s_setprio 1
	v_mfma_f32_16x16x32_bf16 v[52:55], v[164:167], v[180:183], v[52:55]
	v_mfma_f32_16x16x32_bf16 v[48:51], v[172:175], v[180:183], v[48:51]
	v_mfma_f32_16x16x32_bf16 v[52:55], v[168:171], v[184:187], v[52:55]
	v_mfma_f32_16x16x32_bf16 v[48:51], v[176:179], v[184:187], v[48:51]
	s_setprio 0
	s_barrier
	s_add_i32 s52, s52, 2
	s_cmp_gt_u32 s52, 13
	s_mov_b64 s[20:21], s[22:23]
	s_cbranch_scc0 .LBB0_227
	s_and_b64 vcc, exec, s[14:15]
	s_cbranch_vccz .LBB0_230
	s_barrier
